# K loops: the LDS-DMA stage loads of each phase are issued before its ds_reads
# baseline (speedup 1.0000x reference)
.LBB0_236:
	ds_read_b128 v[144:147], v160
	ds_read_b128 v[148:151], v161
	ds_read_b128 v[178:181], v163
	ds_read_b128 v[182:185], v164
	s_add_i32 s14, s2, 2
	s_add_u32 s8, s6, 0x80
	s_addc_u32 s3, s7, 0
	s_cmp_eq_u32 s56, s2
	s_cselect_b32 s2, s62, s8
	s_cselect_b32 s3, s63, s3
	s_cselect_b32 s9, s1, s11
	s_cselect_b32 s8, s0, s10
	s_mov_b32 m0, s61
	s_nop 0
	global_load_lds_dwordx4 v136, s[6:7]
	s_mov_b32 m0, s64
	s_nop 0
	global_load_lds_dwordx4 v138, s[6:7]
	ds_read_b128 v[186:189], v158
	ds_read_b128 v[190:193], v158 offset:1024
	ds_read_b128 v[194:197], v158 offset:2048
	ds_read_b128 v[198:201], v158 offset:3072
	ds_read_b128 v[202:205], v158 offset:4096
	ds_read_b128 v[206:209], v158 offset:5120
	ds_read_b128 v[210:213], v158 offset:6144
	ds_read_b128 v[214:217], v158 offset:7168
	s_waitcnt lgkmcnt(8)
	s_barrier
	s_waitcnt lgkmcnt(0)
	s_waitcnt lgkmcnt(0)
	v_mfma_f32_16x16x32_bf16 v[126:129], v[144:147], v[186:189], v[126:129]
	v_mfma_f32_16x16x32_bf16 v[122:125], v[178:181], v[186:189], v[122:125]
	v_mfma_f32_16x16x32_bf16 v[110:113], v[144:147], v[194:197], v[110:113]
	v_mfma_f32_16x16x32_bf16 v[106:109], v[178:181], v[194:197], v[106:109]
	v_mfma_f32_16x16x32_bf16 v[94:97], v[144:147], v[202:205], v[94:97]
	v_mfma_f32_16x16x32_bf16 v[90:93], v[178:181], v[202:205], v[90:93]
	v_mfma_f32_16x16x32_bf16 v[78:81], v[144:147], v[210:213], v[78:81]
	v_mfma_f32_16x16x32_bf16 v[74:77], v[178:181], v[210:213], v[74:77]
	v_mfma_f32_16x16x32_bf16 v[126:129], v[148:151], v[190:193], v[126:129]
	v_mfma_f32_16x16x32_bf16 v[122:125], v[182:185], v[190:193], v[122:125]
	v_mfma_f32_16x16x32_bf16 v[110:113], v[148:151], v[198:201], v[110:113]
	v_mfma_f32_16x16x32_bf16 v[106:109], v[182:185], v[198:201], v[106:109]
	v_mfma_f32_16x16x32_bf16 v[94:97], v[148:151], v[206:209], v[94:97]
	v_mfma_f32_16x16x32_bf16 v[90:93], v[182:185], v[206:209], v[90:93]
	v_mfma_f32_16x16x32_bf16 v[78:81], v[148:151], v[214:217], v[78:81]
	v_mfma_f32_16x16x32_bf16 v[74:77], v[182:185], v[214:217], v[74:77]
	s_barrier
	s_mov_b32 m0, s30
	s_nop 0
	global_load_lds_dwordx4 v130, s[8:9]
	s_mov_b32 m0, s31
	s_nop 0
	global_load_lds_dwordx4 v132, s[8:9]
	ds_read_b128 v[218:221], v165
	ds_read_b128 v[222:225], v166
	ds_read_b128 v[226:229], v167
	ds_read_b128 v[230:233], v168
	s_barrier
	s_waitcnt lgkmcnt(0)
	s_waitcnt lgkmcnt(0)
	v_mfma_f32_16x16x32_bf16 v[118:121], v[218:221], v[186:189], v[118:121]
	v_mfma_f32_16x16x32_bf16 v[114:117], v[226:229], v[186:189], v[114:117]
	v_mfma_f32_16x16x32_bf16 v[102:105], v[218:221], v[194:197], v[102:105]
	v_mfma_f32_16x16x32_bf16 v[98:101], v[226:229], v[194:197], v[98:101]
	v_mfma_f32_16x16x32_bf16 v[86:89], v[218:221], v[202:205], v[86:89]
	v_mfma_f32_16x16x32_bf16 v[82:85], v[226:229], v[202:205], v[82:85]
	v_mfma_f32_16x16x32_bf16 v[70:73], v[218:221], v[210:213], v[70:73]
	v_mfma_f32_16x16x32_bf16 v[66:69], v[226:229], v[210:213], v[66:69]
	v_mfma_f32_16x16x32_bf16 v[118:121], v[222:225], v[190:193], v[118:121]
	v_mfma_f32_16x16x32_bf16 v[114:117], v[230:233], v[190:193], v[114:117]
	v_mfma_f32_16x16x32_bf16 v[102:105], v[222:225], v[198:201], v[102:105]
	v_mfma_f32_16x16x32_bf16 v[98:101], v[230:233], v[198:201], v[98:101]
	v_mfma_f32_16x16x32_bf16 v[86:89], v[222:225], v[206:209], v[86:89]
	v_mfma_f32_16x16x32_bf16 v[82:85], v[230:233], v[206:209], v[82:85]
	v_mfma_f32_16x16x32_bf16 v[70:73], v[222:225], v[214:217], v[70:73]
	v_mfma_f32_16x16x32_bf16 v[66:69], v[230:233], v[214:217], v[66:69]
	s_mov_b32 m0, s29
	s_barrier
	global_load_lds_dwordx4 v130, s[2:3]
	s_mov_b32 m0, s33
	s_nop 0
	global_load_lds_dwordx4 v132, s[2:3]
	ds_read_b128 v[186:189], v158 offset:16384
	ds_read_b128 v[190:193], v158 offset:17408
	ds_read_b128 v[194:197], v158 offset:18432
	ds_read_b128 v[198:201], v158 offset:19456
	ds_read_b128 v[202:205], v158 offset:20480
	ds_read_b128 v[206:209], v158 offset:21504
	ds_read_b128 v[210:213], v158 offset:22528
	ds_read_b128 v[214:217], v158 offset:23552
	s_barrier
	s_waitcnt lgkmcnt(0)
	s_waitcnt lgkmcnt(0)
	v_mfma_f32_16x16x32_bf16 v[62:65], v[144:147], v[186:189], v[62:65]
	v_mfma_f32_16x16x32_bf16 v[58:61], v[178:181], v[186:189], v[58:61]
	v_mfma_f32_16x16x32_bf16 v[46:49], v[144:147], v[194:197], v[46:49]
	v_mfma_f32_16x16x32_bf16 v[42:45], v[178:181], v[194:197], v[42:45]
	v_mfma_f32_16x16x32_bf16 v[30:33], v[144:147], v[202:205], v[30:33]
	v_mfma_f32_16x16x32_bf16 v[26:29], v[178:181], v[202:205], v[26:29]
	v_mfma_f32_16x16x32_bf16 v[14:17], v[144:147], v[210:213], v[14:17]
	v_mfma_f32_16x16x32_bf16 v[10:13], v[178:181], v[210:213], v[10:13]
	v_mfma_f32_16x16x32_bf16 v[62:65], v[148:151], v[190:193], v[62:65]
	v_mfma_f32_16x16x32_bf16 v[58:61], v[182:185], v[190:193], v[58:61]
	v_mfma_f32_16x16x32_bf16 v[46:49], v[148:151], v[198:201], v[46:49]
	v_mfma_f32_16x16x32_bf16 v[42:45], v[182:185], v[198:201], v[42:45]
	v_mfma_f32_16x16x32_bf16 v[30:33], v[148:151], v[206:209], v[30:33]
	v_mfma_f32_16x16x32_bf16 v[26:29], v[182:185], v[206:209], v[26:29]
	v_mfma_f32_16x16x32_bf16 v[14:17], v[148:151], v[214:217], v[14:17]
	v_mfma_f32_16x16x32_bf16 v[10:13], v[182:185], v[214:217], v[10:13]
	s_barrier
	s_mov_b32 m0, s34
	s_nop 0
	global_load_lds_dwordx4 v243, s[8:9]
	s_mov_b32 m0, s35
	s_nop 0
	global_load_lds_dwordx4 v242, s[8:9]
	s_waitcnt vmcnt(6)
	s_barrier
	v_mfma_f32_16x16x32_bf16 v[54:57], v[218:221], v[186:189], v[54:57]
	v_mfma_f32_16x16x32_bf16 v[50:53], v[226:229], v[186:189], v[50:53]
	v_mfma_f32_16x16x32_bf16 v[38:41], v[218:221], v[194:197], v[38:41]
	v_mfma_f32_16x16x32_bf16 v[34:37], v[226:229], v[194:197], v[34:37]
	v_mfma_f32_16x16x32_bf16 v[22:25], v[218:221], v[202:205], v[22:25]
	v_mfma_f32_16x16x32_bf16 v[18:21], v[226:229], v[202:205], v[18:21]
	v_mfma_f32_16x16x32_bf16 v[6:9], v[218:221], v[210:213], v[6:9]
	v_mfma_f32_16x16x32_bf16 v[2:5], v[226:229], v[210:213], v[2:5]
	v_mfma_f32_16x16x32_bf16 v[54:57], v[222:225], v[190:193], v[54:57]
	v_mfma_f32_16x16x32_bf16 v[50:53], v[230:233], v[190:193], v[50:53]
	v_mfma_f32_16x16x32_bf16 v[38:41], v[222:225], v[198:201], v[38:41]
	v_mfma_f32_16x16x32_bf16 v[34:37], v[230:233], v[198:201], v[34:37]
	v_mfma_f32_16x16x32_bf16 v[22:25], v[222:225], v[206:209], v[22:25]
	v_mfma_f32_16x16x32_bf16 v[18:21], v[230:233], v[206:209], v[18:21]
	v_mfma_f32_16x16x32_bf16 v[6:9], v[222:225], v[214:217], v[6:9]
	v_mfma_f32_16x16x32_bf16 v[2:5], v[230:233], v[214:217], v[2:5]
	s_barrier
	ds_read_b128 v[144:147], v169
	ds_read_b128 v[148:151], v170
	ds_read_b128 v[178:181], v171
	ds_read_b128 v[182:185], v172
	s_mov_b32 m0, s38
	s_nop 0
	global_load_lds_dwordx4 v243, s[2:3]
	s_mov_b32 m0, s39
	s_nop 0
	global_load_lds_dwordx4 v242, s[2:3]
	ds_read_b128 v[186:189], v158 offset:32768
	ds_read_b128 v[190:193], v158 offset:33792
	ds_read_b128 v[194:197], v158 offset:34816
	ds_read_b128 v[198:201], v158 offset:35840
	ds_read_b128 v[202:205], v158 offset:36864
	ds_read_b128 v[206:209], v158 offset:37888
	ds_read_b128 v[210:213], v158 offset:38912
	ds_read_b128 v[214:217], v158 offset:39936
	s_waitcnt lgkmcnt(8)
	s_barrier
	s_waitcnt lgkmcnt(0)
	s_waitcnt lgkmcnt(0)
	v_mfma_f32_16x16x32_bf16 v[126:129], v[144:147], v[186:189], v[126:129]
	v_mfma_f32_16x16x32_bf16 v[122:125], v[178:181], v[186:189], v[122:125]
	v_mfma_f32_16x16x32_bf16 v[110:113], v[144:147], v[194:197], v[110:113]
	v_mfma_f32_16x16x32_bf16 v[106:109], v[178:181], v[194:197], v[106:109]
	v_mfma_f32_16x16x32_bf16 v[94:97], v[144:147], v[202:205], v[94:97]
	v_mfma_f32_16x16x32_bf16 v[90:93], v[178:181], v[202:205], v[90:93]
	v_mfma_f32_16x16x32_bf16 v[78:81], v[144:147], v[210:213], v[78:81]
	v_mfma_f32_16x16x32_bf16 v[74:77], v[178:181], v[210:213], v[74:77]
	v_mfma_f32_16x16x32_bf16 v[126:129], v[148:151], v[190:193], v[126:129]
	v_mfma_f32_16x16x32_bf16 v[122:125], v[182:185], v[190:193], v[122:125]
	v_mfma_f32_16x16x32_bf16 v[110:113], v[148:151], v[198:201], v[110:113]
	v_mfma_f32_16x16x32_bf16 v[106:109], v[182:185], v[198:201], v[106:109]
	v_mfma_f32_16x16x32_bf16 v[94:97], v[148:151], v[206:209], v[94:97]
	v_mfma_f32_16x16x32_bf16 v[90:93], v[182:185], v[206:209], v[90:93]
	v_mfma_f32_16x16x32_bf16 v[78:81], v[148:151], v[214:217], v[78:81]
	v_mfma_f32_16x16x32_bf16 v[74:77], v[182:185], v[214:217], v[74:77]
	s_barrier
	s_sub_u32 m0, s41, 0x80
	s_nop 0
	global_load_lds_dwordx4 v130, s[8:9] offset:128
	s_sub_u32 m0, s42, 0x80
	s_nop 0
	global_load_lds_dwordx4 v132, s[8:9] offset:128
	ds_read_b128 v[218:221], v173
	ds_read_b128 v[222:225], v174
	ds_read_b128 v[226:229], v175
	ds_read_b128 v[230:233], v176
	s_barrier
	s_waitcnt lgkmcnt(0)
	s_waitcnt lgkmcnt(0)
	v_mfma_f32_16x16x32_bf16 v[118:121], v[218:221], v[186:189], v[118:121]
	v_mfma_f32_16x16x32_bf16 v[114:117], v[226:229], v[186:189], v[114:117]
	v_mfma_f32_16x16x32_bf16 v[102:105], v[218:221], v[194:197], v[102:105]
	v_mfma_f32_16x16x32_bf16 v[98:101], v[226:229], v[194:197], v[98:101]
	v_mfma_f32_16x16x32_bf16 v[86:89], v[218:221], v[202:205], v[86:89]
	v_mfma_f32_16x16x32_bf16 v[82:85], v[226:229], v[202:205], v[82:85]
	v_mfma_f32_16x16x32_bf16 v[70:73], v[218:221], v[210:213], v[70:73]
	v_mfma_f32_16x16x32_bf16 v[66:69], v[226:229], v[210:213], v[66:69]
	v_mfma_f32_16x16x32_bf16 v[118:121], v[222:225], v[190:193], v[118:121]
	v_mfma_f32_16x16x32_bf16 v[114:117], v[230:233], v[190:193], v[114:117]
	v_mfma_f32_16x16x32_bf16 v[102:105], v[222:225], v[198:201], v[102:105]
	v_mfma_f32_16x16x32_bf16 v[98:101], v[230:233], v[198:201], v[98:101]
	v_mfma_f32_16x16x32_bf16 v[86:89], v[222:225], v[206:209], v[86:89]
	v_mfma_f32_16x16x32_bf16 v[82:85], v[230:233], v[206:209], v[82:85]
	v_mfma_f32_16x16x32_bf16 v[70:73], v[222:225], v[214:217], v[70:73]
	v_mfma_f32_16x16x32_bf16 v[66:69], v[230:233], v[214:217], v[66:69]
	s_sub_u32 m0, s43, 0x80
	s_barrier
	global_load_lds_dwordx4 v130, s[2:3] offset:128
	s_sub_u32 m0, s48, 0x80
	s_nop 0
	global_load_lds_dwordx4 v132, s[2:3] offset:128
	ds_read_b128 v[186:189], v158 offset:49152
	ds_read_b128 v[190:193], v158 offset:50176
	ds_read_b128 v[194:197], v158 offset:51200
	ds_read_b128 v[198:201], v158 offset:52224
	ds_read_b128 v[202:205], v158 offset:53248
	ds_read_b128 v[206:209], v158 offset:54272
	ds_read_b128 v[210:213], v158 offset:55296
	ds_read_b128 v[214:217], v158 offset:56320
	s_barrier
	s_waitcnt lgkmcnt(0)
	s_waitcnt lgkmcnt(0)
	v_mfma_f32_16x16x32_bf16 v[62:65], v[144:147], v[186:189], v[62:65]
	v_mfma_f32_16x16x32_bf16 v[58:61], v[178:181], v[186:189], v[58:61]
	v_mfma_f32_16x16x32_bf16 v[46:49], v[144:147], v[194:197], v[46:49]
	v_mfma_f32_16x16x32_bf16 v[42:45], v[178:181], v[194:197], v[42:45]
	v_mfma_f32_16x16x32_bf16 v[30:33], v[144:147], v[202:205], v[30:33]
	v_mfma_f32_16x16x32_bf16 v[26:29], v[178:181], v[202:205], v[26:29]
	v_mfma_f32_16x16x32_bf16 v[14:17], v[144:147], v[210:213], v[14:17]
	v_mfma_f32_16x16x32_bf16 v[10:13], v[178:181], v[210:213], v[10:13]
	v_mfma_f32_16x16x32_bf16 v[62:65], v[148:151], v[190:193], v[62:65]
	v_mfma_f32_16x16x32_bf16 v[58:61], v[182:185], v[190:193], v[58:61]
	v_mfma_f32_16x16x32_bf16 v[46:49], v[148:151], v[198:201], v[46:49]
	v_mfma_f32_16x16x32_bf16 v[42:45], v[182:185], v[198:201], v[42:45]
	v_mfma_f32_16x16x32_bf16 v[30:33], v[148:151], v[206:209], v[30:33]
	v_mfma_f32_16x16x32_bf16 v[26:29], v[182:185], v[206:209], v[26:29]
	v_mfma_f32_16x16x32_bf16 v[14:17], v[148:151], v[214:217], v[14:17]
	v_mfma_f32_16x16x32_bf16 v[10:13], v[182:185], v[214:217], v[10:13]
	s_barrier
	s_sub_u32 m0, s49, 0x80
	s_nop 0
	global_load_lds_dwordx4 v243, s[8:9] offset:128
	s_sub_u32 m0, s50, 0x80
	s_nop 0
	global_load_lds_dwordx4 v242, s[8:9] offset:128
	s_waitcnt vmcnt(6)
	s_barrier
	v_mfma_f32_16x16x32_bf16 v[54:57], v[218:221], v[186:189], v[54:57]
	v_mfma_f32_16x16x32_bf16 v[50:53], v[226:229], v[186:189], v[50:53]
	v_mfma_f32_16x16x32_bf16 v[38:41], v[218:221], v[194:197], v[38:41]
	v_mfma_f32_16x16x32_bf16 v[34:37], v[226:229], v[194:197], v[34:37]
	v_mfma_f32_16x16x32_bf16 v[22:25], v[218:221], v[202:205], v[22:25]
	v_mfma_f32_16x16x32_bf16 v[18:21], v[226:229], v[202:205], v[18:21]
	v_mfma_f32_16x16x32_bf16 v[6:9], v[218:221], v[210:213], v[6:9]
	v_mfma_f32_16x16x32_bf16 v[2:5], v[226:229], v[210:213], v[2:5]
	v_mfma_f32_16x16x32_bf16 v[54:57], v[222:225], v[190:193], v[54:57]
	v_mfma_f32_16x16x32_bf16 v[50:53], v[230:233], v[190:193], v[50:53]
	v_mfma_f32_16x16x32_bf16 v[38:41], v[222:225], v[198:201], v[38:41]
	v_mfma_f32_16x16x32_bf16 v[34:37], v[230:233], v[198:201], v[34:37]
	v_mfma_f32_16x16x32_bf16 v[22:25], v[222:225], v[206:209], v[22:25]
	v_mfma_f32_16x16x32_bf16 v[18:21], v[230:233], v[206:209], v[18:21]
	v_mfma_f32_16x16x32_bf16 v[6:9], v[222:225], v[214:217], v[6:9]
	v_mfma_f32_16x16x32_bf16 v[2:5], v[230:233], v[214:217], v[2:5]
	s_add_u32 s6, s6, 0x100
	s_addc_u32 s7, s7, 0
	s_add_u32 s10, s10, 0x100
	s_addc_u32 s11, s11, 0
	s_cmp_ge_i32 s14, s51
	s_mov_b32 s2, s14
	s_barrier
	s_cbranch_scc0 .LBB0_236

.LBB0_997:
	ds_read_b128 v[142:145], v168
	ds_read_b128 v[146:149], v169
	ds_read_b128 v[150:153], v170
	ds_read_b128 v[154:157], v171
	s_add_i32 s57, s2, 2
	s_add_u32 s26, s24, 0x80
	s_addc_u32 s3, s25, 0
	s_cmp_eq_u32 s46, s2
	s_cselect_b32 s2, s10, s26
	s_cselect_b32 s3, s11, s3
	s_cselect_b32 s27, s1, s37
	s_cselect_b32 s26, s0, s36
	s_mov_b32 m0, s51
	s_nop 0
	global_load_lds_dwordx4 v134, s[24:25]
	s_mov_b32 m0, s52
	s_nop 0
	global_load_lds_dwordx4 v136, s[24:25]
	ds_read_b128 v[186:189], v166
	ds_read_b128 v[190:193], v166 offset:1024
	ds_read_b128 v[194:197], v166 offset:2048
	ds_read_b128 v[198:201], v166 offset:3072
	ds_read_b128 v[202:205], v166 offset:4096
	ds_read_b128 v[206:209], v166 offset:5120
	ds_read_b128 v[210:213], v166 offset:6144
	ds_read_b128 v[214:217], v166 offset:7168
	s_waitcnt lgkmcnt(8)
	s_barrier
	s_waitcnt lgkmcnt(0)
	s_waitcnt lgkmcnt(0)
	v_mfma_f32_16x16x32_bf16 v[126:129], v[142:145], v[186:189], v[126:129]
	v_mfma_f32_16x16x32_bf16 v[122:125], v[150:153], v[186:189], v[122:125]
	v_mfma_f32_16x16x32_bf16 v[110:113], v[142:145], v[194:197], v[110:113]
	v_mfma_f32_16x16x32_bf16 v[106:109], v[150:153], v[194:197], v[106:109]
	v_mfma_f32_16x16x32_bf16 v[94:97], v[142:145], v[202:205], v[94:97]
	v_mfma_f32_16x16x32_bf16 v[90:93], v[150:153], v[202:205], v[90:93]
	v_mfma_f32_16x16x32_bf16 v[78:81], v[142:145], v[210:213], v[78:81]
	v_mfma_f32_16x16x32_bf16 v[74:77], v[150:153], v[210:213], v[74:77]
	v_mfma_f32_16x16x32_bf16 v[126:129], v[146:149], v[190:193], v[126:129]
	v_mfma_f32_16x16x32_bf16 v[122:125], v[154:157], v[190:193], v[122:125]
	v_mfma_f32_16x16x32_bf16 v[110:113], v[146:149], v[198:201], v[110:113]
	v_mfma_f32_16x16x32_bf16 v[106:109], v[154:157], v[198:201], v[106:109]
	v_mfma_f32_16x16x32_bf16 v[94:97], v[146:149], v[206:209], v[94:97]
	v_mfma_f32_16x16x32_bf16 v[90:93], v[154:157], v[206:209], v[90:93]
	v_mfma_f32_16x16x32_bf16 v[78:81], v[146:149], v[214:217], v[78:81]
	v_mfma_f32_16x16x32_bf16 v[74:77], v[154:157], v[214:217], v[74:77]
	s_barrier
	s_mov_b32 m0, s29
	s_nop 0
	global_load_lds_dwordx4 v130, s[26:27]
	s_mov_b32 m0, s30
	s_nop 0
	global_load_lds_dwordx4 v132, s[26:27]
	ds_read_b128 v[218:221], v172
	ds_read_b128 v[222:225], v173
	ds_read_b128 v[226:229], v174
	ds_read_b128 v[230:233], v175
	s_barrier
	s_waitcnt lgkmcnt(0)
	s_waitcnt lgkmcnt(0)
	v_mfma_f32_16x16x32_bf16 v[118:121], v[218:221], v[186:189], v[118:121]
	v_mfma_f32_16x16x32_bf16 v[114:117], v[226:229], v[186:189], v[114:117]
	v_mfma_f32_16x16x32_bf16 v[102:105], v[218:221], v[194:197], v[102:105]
	v_mfma_f32_16x16x32_bf16 v[98:101], v[226:229], v[194:197], v[98:101]
	v_mfma_f32_16x16x32_bf16 v[86:89], v[218:221], v[202:205], v[86:89]
	v_mfma_f32_16x16x32_bf16 v[82:85], v[226:229], v[202:205], v[82:85]
	v_mfma_f32_16x16x32_bf16 v[70:73], v[218:221], v[210:213], v[70:73]
	v_mfma_f32_16x16x32_bf16 v[66:69], v[226:229], v[210:213], v[66:69]
	v_mfma_f32_16x16x32_bf16 v[118:121], v[222:225], v[190:193], v[118:121]
	v_mfma_f32_16x16x32_bf16 v[114:117], v[230:233], v[190:193], v[114:117]
	v_mfma_f32_16x16x32_bf16 v[102:105], v[222:225], v[198:201], v[102:105]
	v_mfma_f32_16x16x32_bf16 v[98:101], v[230:233], v[198:201], v[98:101]
	v_mfma_f32_16x16x32_bf16 v[86:89], v[222:225], v[206:209], v[86:89]
	v_mfma_f32_16x16x32_bf16 v[82:85], v[230:233], v[206:209], v[82:85]
	v_mfma_f32_16x16x32_bf16 v[70:73], v[222:225], v[214:217], v[70:73]
	v_mfma_f32_16x16x32_bf16 v[66:69], v[230:233], v[214:217], v[66:69]
	s_mov_b32 m0, s28
	s_barrier
	global_load_lds_dwordx4 v130, s[2:3]
	s_mov_b32 m0, s31
	s_nop 0
	global_load_lds_dwordx4 v132, s[2:3]
	ds_read_b128 v[186:189], v166 offset:16384
	ds_read_b128 v[190:193], v166 offset:17408
	ds_read_b128 v[194:197], v166 offset:18432
	ds_read_b128 v[198:201], v166 offset:19456
	ds_read_b128 v[202:205], v166 offset:20480
	ds_read_b128 v[206:209], v166 offset:21504
	ds_read_b128 v[210:213], v166 offset:22528
	ds_read_b128 v[214:217], v166 offset:23552
	s_barrier
	s_waitcnt lgkmcnt(0)
	s_waitcnt lgkmcnt(0)
	v_mfma_f32_16x16x32_bf16 v[62:65], v[142:145], v[186:189], v[62:65]
	v_mfma_f32_16x16x32_bf16 v[58:61], v[150:153], v[186:189], v[58:61]
	v_mfma_f32_16x16x32_bf16 v[46:49], v[142:145], v[194:197], v[46:49]
	v_mfma_f32_16x16x32_bf16 v[42:45], v[150:153], v[194:197], v[42:45]
	v_mfma_f32_16x16x32_bf16 v[30:33], v[142:145], v[202:205], v[30:33]
	v_mfma_f32_16x16x32_bf16 v[26:29], v[150:153], v[202:205], v[26:29]
	v_mfma_f32_16x16x32_bf16 v[14:17], v[142:145], v[210:213], v[14:17]
	v_mfma_f32_16x16x32_bf16 v[10:13], v[150:153], v[210:213], v[10:13]
	v_mfma_f32_16x16x32_bf16 v[62:65], v[146:149], v[190:193], v[62:65]
	v_mfma_f32_16x16x32_bf16 v[58:61], v[154:157], v[190:193], v[58:61]
	v_mfma_f32_16x16x32_bf16 v[46:49], v[146:149], v[198:201], v[46:49]
	v_mfma_f32_16x16x32_bf16 v[42:45], v[154:157], v[198:201], v[42:45]
	v_mfma_f32_16x16x32_bf16 v[30:33], v[146:149], v[206:209], v[30:33]
	v_mfma_f32_16x16x32_bf16 v[26:29], v[154:157], v[206:209], v[26:29]
	v_mfma_f32_16x16x32_bf16 v[14:17], v[146:149], v[214:217], v[14:17]
	v_mfma_f32_16x16x32_bf16 v[10:13], v[154:157], v[214:217], v[10:13]
	s_barrier
	s_mov_b32 m0, s33
	s_nop 0
	global_load_lds_dwordx4 v243, s[26:27]
	s_mov_b32 m0, s34
	s_nop 0
	global_load_lds_dwordx4 v242, s[26:27]
	s_waitcnt vmcnt(6)
	s_barrier
	v_mfma_f32_16x16x32_bf16 v[54:57], v[218:221], v[186:189], v[54:57]
	v_mfma_f32_16x16x32_bf16 v[50:53], v[226:229], v[186:189], v[50:53]
	v_mfma_f32_16x16x32_bf16 v[38:41], v[218:221], v[194:197], v[38:41]
	v_mfma_f32_16x16x32_bf16 v[34:37], v[226:229], v[194:197], v[34:37]
	v_mfma_f32_16x16x32_bf16 v[22:25], v[218:221], v[202:205], v[22:25]
	v_mfma_f32_16x16x32_bf16 v[18:21], v[226:229], v[202:205], v[18:21]
	v_mfma_f32_16x16x32_bf16 v[6:9], v[218:221], v[210:213], v[6:9]
	v_mfma_f32_16x16x32_bf16 v[2:5], v[226:229], v[210:213], v[2:5]
	v_mfma_f32_16x16x32_bf16 v[54:57], v[222:225], v[190:193], v[54:57]
	v_mfma_f32_16x16x32_bf16 v[50:53], v[230:233], v[190:193], v[50:53]
	v_mfma_f32_16x16x32_bf16 v[38:41], v[222:225], v[198:201], v[38:41]
	v_mfma_f32_16x16x32_bf16 v[34:37], v[230:233], v[198:201], v[34:37]
	v_mfma_f32_16x16x32_bf16 v[22:25], v[222:225], v[206:209], v[22:25]
	v_mfma_f32_16x16x32_bf16 v[18:21], v[230:233], v[206:209], v[18:21]
	v_mfma_f32_16x16x32_bf16 v[6:9], v[222:225], v[214:217], v[6:9]
	v_mfma_f32_16x16x32_bf16 v[2:5], v[230:233], v[214:217], v[2:5]
	s_barrier
	ds_read_b128 v[142:145], v176
	ds_read_b128 v[146:149], v177
	ds_read_b128 v[150:153], v178
	ds_read_b128 v[154:157], v179
	s_mov_b32 m0, s35
	s_nop 0
	global_load_lds_dwordx4 v243, s[2:3]
	s_mov_b32 m0, s38
	s_nop 0
	global_load_lds_dwordx4 v242, s[2:3]
	ds_read_b128 v[186:189], v166 offset:32768
	ds_read_b128 v[190:193], v166 offset:33792
	ds_read_b128 v[194:197], v166 offset:34816
	ds_read_b128 v[198:201], v166 offset:35840
	ds_read_b128 v[202:205], v166 offset:36864
	ds_read_b128 v[206:209], v166 offset:37888
	ds_read_b128 v[210:213], v166 offset:38912
	ds_read_b128 v[214:217], v166 offset:39936
	s_waitcnt lgkmcnt(8)
	s_barrier
	s_waitcnt lgkmcnt(0)
	s_waitcnt lgkmcnt(0)
	v_mfma_f32_16x16x32_bf16 v[126:129], v[142:145], v[186:189], v[126:129]
	v_mfma_f32_16x16x32_bf16 v[122:125], v[150:153], v[186:189], v[122:125]
	v_mfma_f32_16x16x32_bf16 v[110:113], v[142:145], v[194:197], v[110:113]
	v_mfma_f32_16x16x32_bf16 v[106:109], v[150:153], v[194:197], v[106:109]
	v_mfma_f32_16x16x32_bf16 v[94:97], v[142:145], v[202:205], v[94:97]
	v_mfma_f32_16x16x32_bf16 v[90:93], v[150:153], v[202:205], v[90:93]
	v_mfma_f32_16x16x32_bf16 v[78:81], v[142:145], v[210:213], v[78:81]
	v_mfma_f32_16x16x32_bf16 v[74:77], v[150:153], v[210:213], v[74:77]
	v_mfma_f32_16x16x32_bf16 v[126:129], v[146:149], v[190:193], v[126:129]
	v_mfma_f32_16x16x32_bf16 v[122:125], v[154:157], v[190:193], v[122:125]
	v_mfma_f32_16x16x32_bf16 v[110:113], v[146:149], v[198:201], v[110:113]
	v_mfma_f32_16x16x32_bf16 v[106:109], v[154:157], v[198:201], v[106:109]
	v_mfma_f32_16x16x32_bf16 v[94:97], v[146:149], v[206:209], v[94:97]
	v_mfma_f32_16x16x32_bf16 v[90:93], v[154:157], v[206:209], v[90:93]
	v_mfma_f32_16x16x32_bf16 v[78:81], v[146:149], v[214:217], v[78:81]
	v_mfma_f32_16x16x32_bf16 v[74:77], v[154:157], v[214:217], v[74:77]
	s_barrier
	s_sub_u32 m0, s39, 0x80
	s_nop 0
	global_load_lds_dwordx4 v130, s[26:27] offset:128
	s_sub_u32 m0, s40, 0x80
	s_nop 0
	global_load_lds_dwordx4 v132, s[26:27] offset:128
	ds_read_b128 v[218:221], v180
	ds_read_b128 v[222:225], v181
	ds_read_b128 v[226:229], v182
	ds_read_b128 v[230:233], v183
	s_barrier
	s_waitcnt lgkmcnt(0)
	s_waitcnt lgkmcnt(0)
	v_mfma_f32_16x16x32_bf16 v[118:121], v[218:221], v[186:189], v[118:121]
	v_mfma_f32_16x16x32_bf16 v[114:117], v[226:229], v[186:189], v[114:117]
	v_mfma_f32_16x16x32_bf16 v[102:105], v[218:221], v[194:197], v[102:105]
	v_mfma_f32_16x16x32_bf16 v[98:101], v[226:229], v[194:197], v[98:101]
	v_mfma_f32_16x16x32_bf16 v[86:89], v[218:221], v[202:205], v[86:89]
	v_mfma_f32_16x16x32_bf16 v[82:85], v[226:229], v[202:205], v[82:85]
	v_mfma_f32_16x16x32_bf16 v[70:73], v[218:221], v[210:213], v[70:73]
	v_mfma_f32_16x16x32_bf16 v[66:69], v[226:229], v[210:213], v[66:69]
	v_mfma_f32_16x16x32_bf16 v[118:121], v[222:225], v[190:193], v[118:121]
	v_mfma_f32_16x16x32_bf16 v[114:117], v[230:233], v[190:193], v[114:117]
	v_mfma_f32_16x16x32_bf16 v[102:105], v[222:225], v[198:201], v[102:105]
	v_mfma_f32_16x16x32_bf16 v[98:101], v[230:233], v[198:201], v[98:101]
	v_mfma_f32_16x16x32_bf16 v[86:89], v[222:225], v[206:209], v[86:89]
	v_mfma_f32_16x16x32_bf16 v[82:85], v[230:233], v[206:209], v[82:85]
	v_mfma_f32_16x16x32_bf16 v[70:73], v[222:225], v[214:217], v[70:73]
	v_mfma_f32_16x16x32_bf16 v[66:69], v[230:233], v[214:217], v[66:69]
	s_sub_u32 m0, s41, 0x80
	s_barrier
	global_load_lds_dwordx4 v130, s[2:3] offset:128
	s_sub_u32 m0, s42, 0x80
	s_nop 0
	global_load_lds_dwordx4 v132, s[2:3] offset:128
	ds_read_b128 v[186:189], v166 offset:49152
	ds_read_b128 v[190:193], v166 offset:50176
	ds_read_b128 v[194:197], v166 offset:51200
	ds_read_b128 v[198:201], v166 offset:52224
	ds_read_b128 v[202:205], v166 offset:53248
	ds_read_b128 v[206:209], v166 offset:54272
	ds_read_b128 v[210:213], v166 offset:55296
	ds_read_b128 v[214:217], v166 offset:56320
	s_barrier
	s_waitcnt lgkmcnt(0)
	s_waitcnt lgkmcnt(0)
	v_mfma_f32_16x16x32_bf16 v[62:65], v[142:145], v[186:189], v[62:65]
	v_mfma_f32_16x16x32_bf16 v[58:61], v[150:153], v[186:189], v[58:61]
	v_mfma_f32_16x16x32_bf16 v[46:49], v[142:145], v[194:197], v[46:49]
	v_mfma_f32_16x16x32_bf16 v[42:45], v[150:153], v[194:197], v[42:45]
	v_mfma_f32_16x16x32_bf16 v[30:33], v[142:145], v[202:205], v[30:33]
	v_mfma_f32_16x16x32_bf16 v[26:29], v[150:153], v[202:205], v[26:29]
	v_mfma_f32_16x16x32_bf16 v[14:17], v[142:145], v[210:213], v[14:17]
	v_mfma_f32_16x16x32_bf16 v[10:13], v[150:153], v[210:213], v[10:13]
	v_mfma_f32_16x16x32_bf16 v[62:65], v[146:149], v[190:193], v[62:65]
	v_mfma_f32_16x16x32_bf16 v[58:61], v[154:157], v[190:193], v[58:61]
	v_mfma_f32_16x16x32_bf16 v[46:49], v[146:149], v[198:201], v[46:49]
	v_mfma_f32_16x16x32_bf16 v[42:45], v[154:157], v[198:201], v[42:45]
	v_mfma_f32_16x16x32_bf16 v[30:33], v[146:149], v[206:209], v[30:33]
	v_mfma_f32_16x16x32_bf16 v[26:29], v[154:157], v[206:209], v[26:29]
	v_mfma_f32_16x16x32_bf16 v[14:17], v[146:149], v[214:217], v[14:17]
	v_mfma_f32_16x16x32_bf16 v[10:13], v[154:157], v[214:217], v[10:13]
	s_barrier
	s_sub_u32 m0, s43, 0x80
	s_nop 0
	global_load_lds_dwordx4 v243, s[26:27] offset:128
	s_sub_u32 m0, s44, 0x80
	s_nop 0
	global_load_lds_dwordx4 v242, s[26:27] offset:128
	s_waitcnt vmcnt(6)
	s_barrier
	v_mfma_f32_16x16x32_bf16 v[54:57], v[218:221], v[186:189], v[54:57]
	v_mfma_f32_16x16x32_bf16 v[50:53], v[226:229], v[186:189], v[50:53]
	v_mfma_f32_16x16x32_bf16 v[38:41], v[218:221], v[194:197], v[38:41]
	v_mfma_f32_16x16x32_bf16 v[34:37], v[226:229], v[194:197], v[34:37]
	v_mfma_f32_16x16x32_bf16 v[22:25], v[218:221], v[202:205], v[22:25]
	v_mfma_f32_16x16x32_bf16 v[18:21], v[226:229], v[202:205], v[18:21]
	v_mfma_f32_16x16x32_bf16 v[6:9], v[218:221], v[210:213], v[6:9]
	v_mfma_f32_16x16x32_bf16 v[2:5], v[226:229], v[210:213], v[2:5]
	v_mfma_f32_16x16x32_bf16 v[54:57], v[222:225], v[190:193], v[54:57]
	v_mfma_f32_16x16x32_bf16 v[50:53], v[230:233], v[190:193], v[50:53]
	v_mfma_f32_16x16x32_bf16 v[38:41], v[222:225], v[198:201], v[38:41]
	v_mfma_f32_16x16x32_bf16 v[34:37], v[230:233], v[198:201], v[34:37]
	v_mfma_f32_16x16x32_bf16 v[22:25], v[222:225], v[206:209], v[22:25]
	v_mfma_f32_16x16x32_bf16 v[18:21], v[230:233], v[206:209], v[18:21]
	v_mfma_f32_16x16x32_bf16 v[6:9], v[222:225], v[214:217], v[6:9]
	v_mfma_f32_16x16x32_bf16 v[2:5], v[230:233], v[214:217], v[2:5]
	s_add_u32 s24, s24, 0x100
	s_addc_u32 s25, s25, 0
	s_add_u32 s36, s36, 0x100
	s_addc_u32 s37, s37, 0
	s_cmp_ge_i32 s57, s45
	s_mov_b32 s2, s57
	s_barrier
	s_cbranch_scc0 .LBB0_997

.LBB0_1104:
	ds_read_b128 v[122:125], v185
	ds_read_b128 v[126:129], v186
	ds_read_b128 v[138:141], v187
	ds_read_b128 v[142:145], v188
	s_add_i32 s36, s2, 2
	s_add_u32 s26, s0, 0x80
	s_addc_u32 s3, s1, 0
	s_cmp_eq_u32 s58, s2
	s_cselect_b32 s2, s8, s26
	s_cselect_b32 s3, s9, s3
	s_cselect_b32 s27, s55, s29
	s_cselect_b32 s26, s54, s28
	s_mov_b32 m0, s61
	s_nop 0
	global_load_lds_dwordx4 v168, s[0:1]
	s_mov_b32 m0, s62
	s_nop 0
	global_load_lds_dwordx4 v170, s[0:1]
	ds_read_b128 v[146:149], v183
	ds_read_b128 v[150:153], v183 offset:1024
	ds_read_b128 v[154:157], v183 offset:2048
	ds_read_b128 v[158:161], v183 offset:3072
	ds_read_b128 v[176:179], v183 offset:4096
	ds_read_b128 v[202:205], v183 offset:5120
	ds_read_b128 v[206:209], v183 offset:6144
	ds_read_b128 v[210:213], v183 offset:7168
	s_waitcnt lgkmcnt(8)
	s_barrier
	s_waitcnt lgkmcnt(0)
	s_waitcnt lgkmcnt(0)
	v_mfma_f32_16x16x32_bf16 v[134:137], v[122:125], v[146:149], v[134:137]
	v_mfma_f32_16x16x32_bf16 v[118:121], v[138:141], v[146:149], v[118:121]
	v_mfma_f32_16x16x32_bf16 v[110:113], v[122:125], v[154:157], v[110:113]
	v_mfma_f32_16x16x32_bf16 v[102:105], v[138:141], v[154:157], v[102:105]
	v_mfma_f32_16x16x32_bf16 v[94:97], v[122:125], v[176:179], v[94:97]
	v_mfma_f32_16x16x32_bf16 v[86:89], v[138:141], v[176:179], v[86:89]
	v_mfma_f32_16x16x32_bf16 v[78:81], v[122:125], v[206:209], v[78:81]
	v_mfma_f32_16x16x32_bf16 v[70:73], v[138:141], v[206:209], v[70:73]
	v_mfma_f32_16x16x32_bf16 v[134:137], v[126:129], v[150:153], v[134:137]
	v_mfma_f32_16x16x32_bf16 v[118:121], v[142:145], v[150:153], v[118:121]
	v_mfma_f32_16x16x32_bf16 v[110:113], v[126:129], v[158:161], v[110:113]
	v_mfma_f32_16x16x32_bf16 v[102:105], v[142:145], v[158:161], v[102:105]
	v_mfma_f32_16x16x32_bf16 v[94:97], v[126:129], v[202:205], v[94:97]
	v_mfma_f32_16x16x32_bf16 v[86:89], v[142:145], v[202:205], v[86:89]
	v_mfma_f32_16x16x32_bf16 v[78:81], v[126:129], v[210:213], v[78:81]
	v_mfma_f32_16x16x32_bf16 v[70:73], v[142:145], v[210:213], v[70:73]
	s_barrier
	s_mov_b32 m0, s35
	s_nop 0
	global_load_lds_dwordx4 v166, s[26:27]
	s_mov_b32 m0, s38
	s_nop 0
	global_load_lds_dwordx4 v164, s[26:27]
	ds_read_b128 v[214:217], v189
	ds_read_b128 v[218:221], v190
	ds_read_b128 v[222:225], v191
	ds_read_b128 v[226:229], v192
	s_barrier
	s_waitcnt lgkmcnt(0)
	s_waitcnt lgkmcnt(0)
	v_mfma_f32_16x16x32_bf16 v[130:133], v[214:217], v[146:149], v[130:133]
	v_mfma_f32_16x16x32_bf16 v[114:117], v[222:225], v[146:149], v[114:117]
	v_mfma_f32_16x16x32_bf16 v[106:109], v[214:217], v[154:157], v[106:109]
	v_mfma_f32_16x16x32_bf16 v[98:101], v[222:225], v[154:157], v[98:101]
	v_mfma_f32_16x16x32_bf16 v[90:93], v[214:217], v[176:179], v[90:93]
	v_mfma_f32_16x16x32_bf16 v[82:85], v[222:225], v[176:179], v[82:85]
	v_mfma_f32_16x16x32_bf16 v[74:77], v[214:217], v[206:209], v[74:77]
	v_mfma_f32_16x16x32_bf16 v[66:69], v[222:225], v[206:209], v[66:69]
	v_mfma_f32_16x16x32_bf16 v[130:133], v[218:221], v[150:153], v[130:133]
	v_mfma_f32_16x16x32_bf16 v[114:117], v[226:229], v[150:153], v[114:117]
	v_mfma_f32_16x16x32_bf16 v[106:109], v[218:221], v[158:161], v[106:109]
	v_mfma_f32_16x16x32_bf16 v[98:101], v[226:229], v[158:161], v[98:101]
	v_mfma_f32_16x16x32_bf16 v[90:93], v[218:221], v[202:205], v[90:93]
	v_mfma_f32_16x16x32_bf16 v[82:85], v[226:229], v[202:205], v[82:85]
	v_mfma_f32_16x16x32_bf16 v[74:77], v[218:221], v[210:213], v[74:77]
	v_mfma_f32_16x16x32_bf16 v[66:69], v[226:229], v[210:213], v[66:69]
	s_mov_b32 m0, s31
	s_barrier
	global_load_lds_dwordx4 v166, s[2:3]
	s_mov_b32 m0, s39
	s_nop 0
	global_load_lds_dwordx4 v164, s[2:3]
	ds_read_b128 v[146:149], v183 offset:16384
	ds_read_b128 v[150:153], v183 offset:17408
	ds_read_b128 v[154:157], v183 offset:18432
	ds_read_b128 v[158:161], v183 offset:19456
	ds_read_b128 v[176:179], v183 offset:20480
	ds_read_b128 v[202:205], v183 offset:21504
	ds_read_b128 v[206:209], v183 offset:22528
	ds_read_b128 v[210:213], v183 offset:23552
	s_barrier
	s_waitcnt lgkmcnt(0)
	s_waitcnt lgkmcnt(0)
	v_mfma_f32_16x16x32_bf16 v[62:65], v[122:125], v[146:149], v[62:65]
	v_mfma_f32_16x16x32_bf16 v[54:57], v[138:141], v[146:149], v[54:57]
	v_mfma_f32_16x16x32_bf16 v[46:49], v[122:125], v[154:157], v[46:49]
	v_mfma_f32_16x16x32_bf16 v[38:41], v[138:141], v[154:157], v[38:41]
	v_mfma_f32_16x16x32_bf16 v[30:33], v[122:125], v[176:179], v[30:33]
	v_mfma_f32_16x16x32_bf16 v[22:25], v[138:141], v[176:179], v[22:25]
	v_mfma_f32_16x16x32_bf16 v[14:17], v[122:125], v[206:209], v[14:17]
	v_mfma_f32_16x16x32_bf16 v[6:9], v[138:141], v[206:209], v[6:9]
	v_mfma_f32_16x16x32_bf16 v[62:65], v[126:129], v[150:153], v[62:65]
	v_mfma_f32_16x16x32_bf16 v[54:57], v[142:145], v[150:153], v[54:57]
	v_mfma_f32_16x16x32_bf16 v[46:49], v[126:129], v[158:161], v[46:49]
	v_mfma_f32_16x16x32_bf16 v[38:41], v[142:145], v[158:161], v[38:41]
	v_mfma_f32_16x16x32_bf16 v[30:33], v[126:129], v[202:205], v[30:33]
	v_mfma_f32_16x16x32_bf16 v[22:25], v[142:145], v[202:205], v[22:25]
	v_mfma_f32_16x16x32_bf16 v[14:17], v[126:129], v[210:213], v[14:17]
	v_mfma_f32_16x16x32_bf16 v[6:9], v[142:145], v[210:213], v[6:9]
	s_barrier
	s_mov_b32 m0, s40
	s_nop 0
	global_load_lds_dwordx4 v240, s[26:27]
	s_mov_b32 m0, s41
	s_nop 0
	global_load_lds_dwordx4 v241, s[26:27]
	s_waitcnt vmcnt(6)
	s_barrier
	v_mfma_f32_16x16x32_bf16 v[58:61], v[214:217], v[146:149], v[58:61]
	v_mfma_f32_16x16x32_bf16 v[50:53], v[222:225], v[146:149], v[50:53]
	v_mfma_f32_16x16x32_bf16 v[42:45], v[214:217], v[154:157], v[42:45]
	v_mfma_f32_16x16x32_bf16 v[34:37], v[222:225], v[154:157], v[34:37]
	v_mfma_f32_16x16x32_bf16 v[26:29], v[214:217], v[176:179], v[26:29]
	v_mfma_f32_16x16x32_bf16 v[18:21], v[222:225], v[176:179], v[18:21]
	v_mfma_f32_16x16x32_bf16 v[10:13], v[214:217], v[206:209], v[10:13]
	v_mfma_f32_16x16x32_bf16 v[2:5], v[222:225], v[206:209], v[2:5]
	v_mfma_f32_16x16x32_bf16 v[58:61], v[218:221], v[150:153], v[58:61]
	v_mfma_f32_16x16x32_bf16 v[50:53], v[226:229], v[150:153], v[50:53]
	v_mfma_f32_16x16x32_bf16 v[42:45], v[218:221], v[158:161], v[42:45]
	v_mfma_f32_16x16x32_bf16 v[34:37], v[226:229], v[158:161], v[34:37]
	v_mfma_f32_16x16x32_bf16 v[26:29], v[218:221], v[202:205], v[26:29]
	v_mfma_f32_16x16x32_bf16 v[18:21], v[226:229], v[202:205], v[18:21]
	v_mfma_f32_16x16x32_bf16 v[10:13], v[218:221], v[210:213], v[10:13]
	v_mfma_f32_16x16x32_bf16 v[2:5], v[226:229], v[210:213], v[2:5]
	s_barrier
	ds_read_b128 v[122:125], v193
	ds_read_b128 v[126:129], v194
	ds_read_b128 v[138:141], v195
	ds_read_b128 v[142:145], v196
	s_mov_b32 m0, s42
	s_nop 0
	global_load_lds_dwordx4 v240, s[2:3]
	s_mov_b32 m0, s43
	s_nop 0
	global_load_lds_dwordx4 v241, s[2:3]
	ds_read_b128 v[146:149], v183 offset:32768
	ds_read_b128 v[150:153], v183 offset:33792
	ds_read_b128 v[154:157], v183 offset:34816
	ds_read_b128 v[158:161], v183 offset:35840
	ds_read_b128 v[176:179], v183 offset:36864
	ds_read_b128 v[202:205], v183 offset:37888
	ds_read_b128 v[206:209], v183 offset:38912
	ds_read_b128 v[210:213], v183 offset:39936
	s_waitcnt lgkmcnt(8)
	s_barrier
	s_waitcnt lgkmcnt(0)
	s_waitcnt lgkmcnt(0)
	v_mfma_f32_16x16x32_bf16 v[134:137], v[122:125], v[146:149], v[134:137]
	v_mfma_f32_16x16x32_bf16 v[118:121], v[138:141], v[146:149], v[118:121]
	v_mfma_f32_16x16x32_bf16 v[110:113], v[122:125], v[154:157], v[110:113]
	v_mfma_f32_16x16x32_bf16 v[102:105], v[138:141], v[154:157], v[102:105]
	v_mfma_f32_16x16x32_bf16 v[94:97], v[122:125], v[176:179], v[94:97]
	v_mfma_f32_16x16x32_bf16 v[86:89], v[138:141], v[176:179], v[86:89]
	v_mfma_f32_16x16x32_bf16 v[78:81], v[122:125], v[206:209], v[78:81]
	v_mfma_f32_16x16x32_bf16 v[70:73], v[138:141], v[206:209], v[70:73]
	v_mfma_f32_16x16x32_bf16 v[134:137], v[126:129], v[150:153], v[134:137]
	v_mfma_f32_16x16x32_bf16 v[118:121], v[142:145], v[150:153], v[118:121]
	v_mfma_f32_16x16x32_bf16 v[110:113], v[126:129], v[158:161], v[110:113]
	v_mfma_f32_16x16x32_bf16 v[102:105], v[142:145], v[158:161], v[102:105]
	v_mfma_f32_16x16x32_bf16 v[94:97], v[126:129], v[202:205], v[94:97]
	v_mfma_f32_16x16x32_bf16 v[86:89], v[142:145], v[202:205], v[86:89]
	v_mfma_f32_16x16x32_bf16 v[78:81], v[126:129], v[210:213], v[78:81]
	v_mfma_f32_16x16x32_bf16 v[70:73], v[142:145], v[210:213], v[70:73]
	s_barrier
	s_sub_u32 m0, s48, 0x80
	s_nop 0
	global_load_lds_dwordx4 v166, s[26:27] offset:128
	s_sub_u32 m0, s49, 0x80
	s_nop 0
	global_load_lds_dwordx4 v164, s[26:27] offset:128
	ds_read_b128 v[214:217], v197
	ds_read_b128 v[218:221], v198
	ds_read_b128 v[222:225], v199
	ds_read_b128 v[226:229], v200
	s_barrier
	s_waitcnt lgkmcnt(0)
	s_waitcnt lgkmcnt(0)
	v_mfma_f32_16x16x32_bf16 v[130:133], v[214:217], v[146:149], v[130:133]
	v_mfma_f32_16x16x32_bf16 v[114:117], v[222:225], v[146:149], v[114:117]
	v_mfma_f32_16x16x32_bf16 v[106:109], v[214:217], v[154:157], v[106:109]
	v_mfma_f32_16x16x32_bf16 v[98:101], v[222:225], v[154:157], v[98:101]
	v_mfma_f32_16x16x32_bf16 v[90:93], v[214:217], v[176:179], v[90:93]
	v_mfma_f32_16x16x32_bf16 v[82:85], v[222:225], v[176:179], v[82:85]
	v_mfma_f32_16x16x32_bf16 v[74:77], v[214:217], v[206:209], v[74:77]
	v_mfma_f32_16x16x32_bf16 v[66:69], v[222:225], v[206:209], v[66:69]
	v_mfma_f32_16x16x32_bf16 v[130:133], v[218:221], v[150:153], v[130:133]
	v_mfma_f32_16x16x32_bf16 v[114:117], v[226:229], v[150:153], v[114:117]
	v_mfma_f32_16x16x32_bf16 v[106:109], v[218:221], v[158:161], v[106:109]
	v_mfma_f32_16x16x32_bf16 v[98:101], v[226:229], v[158:161], v[98:101]
	v_mfma_f32_16x16x32_bf16 v[90:93], v[218:221], v[202:205], v[90:93]
	v_mfma_f32_16x16x32_bf16 v[82:85], v[226:229], v[202:205], v[82:85]
	v_mfma_f32_16x16x32_bf16 v[74:77], v[218:221], v[210:213], v[74:77]
	v_mfma_f32_16x16x32_bf16 v[66:69], v[226:229], v[210:213], v[66:69]
	s_sub_u32 m0, s50, 0x80
	s_barrier
	global_load_lds_dwordx4 v166, s[2:3] offset:128
	s_sub_u32 m0, s51, 0x80
	s_nop 0
	global_load_lds_dwordx4 v164, s[2:3] offset:128
	ds_read_b128 v[146:149], v183 offset:49152
	ds_read_b128 v[150:153], v183 offset:50176
	ds_read_b128 v[154:157], v183 offset:51200
	ds_read_b128 v[158:161], v183 offset:52224
	ds_read_b128 v[176:179], v183 offset:53248
	ds_read_b128 v[202:205], v183 offset:54272
	ds_read_b128 v[206:209], v183 offset:55296
	ds_read_b128 v[210:213], v183 offset:56320
	s_barrier
	s_waitcnt lgkmcnt(0)
	s_waitcnt lgkmcnt(0)
	v_mfma_f32_16x16x32_bf16 v[62:65], v[122:125], v[146:149], v[62:65]
	v_mfma_f32_16x16x32_bf16 v[54:57], v[138:141], v[146:149], v[54:57]
	v_mfma_f32_16x16x32_bf16 v[46:49], v[122:125], v[154:157], v[46:49]
	v_mfma_f32_16x16x32_bf16 v[38:41], v[138:141], v[154:157], v[38:41]
	v_mfma_f32_16x16x32_bf16 v[30:33], v[122:125], v[176:179], v[30:33]
	v_mfma_f32_16x16x32_bf16 v[22:25], v[138:141], v[176:179], v[22:25]
	v_mfma_f32_16x16x32_bf16 v[14:17], v[122:125], v[206:209], v[14:17]
	v_mfma_f32_16x16x32_bf16 v[6:9], v[138:141], v[206:209], v[6:9]
	v_mfma_f32_16x16x32_bf16 v[62:65], v[126:129], v[150:153], v[62:65]
	v_mfma_f32_16x16x32_bf16 v[54:57], v[142:145], v[150:153], v[54:57]
	v_mfma_f32_16x16x32_bf16 v[46:49], v[126:129], v[158:161], v[46:49]
	v_mfma_f32_16x16x32_bf16 v[38:41], v[142:145], v[158:161], v[38:41]
	v_mfma_f32_16x16x32_bf16 v[30:33], v[126:129], v[202:205], v[30:33]
	v_mfma_f32_16x16x32_bf16 v[22:25], v[142:145], v[202:205], v[22:25]
	v_mfma_f32_16x16x32_bf16 v[14:17], v[126:129], v[210:213], v[14:17]
	v_mfma_f32_16x16x32_bf16 v[6:9], v[142:145], v[210:213], v[6:9]
	s_barrier
	s_sub_u32 m0, s53, 0x80
	s_nop 0
	global_load_lds_dwordx4 v240, s[26:27] offset:128
	s_sub_u32 m0, s56, 0x80
	s_nop 0
	global_load_lds_dwordx4 v241, s[26:27] offset:128
	s_waitcnt vmcnt(6)
	s_barrier
	v_mfma_f32_16x16x32_bf16 v[58:61], v[214:217], v[146:149], v[58:61]
	v_mfma_f32_16x16x32_bf16 v[50:53], v[222:225], v[146:149], v[50:53]
	v_mfma_f32_16x16x32_bf16 v[42:45], v[214:217], v[154:157], v[42:45]
	v_mfma_f32_16x16x32_bf16 v[34:37], v[222:225], v[154:157], v[34:37]
	v_mfma_f32_16x16x32_bf16 v[26:29], v[214:217], v[176:179], v[26:29]
	v_mfma_f32_16x16x32_bf16 v[18:21], v[222:225], v[176:179], v[18:21]
	v_mfma_f32_16x16x32_bf16 v[10:13], v[214:217], v[206:209], v[10:13]
	v_mfma_f32_16x16x32_bf16 v[2:5], v[222:225], v[206:209], v[2:5]
	v_mfma_f32_16x16x32_bf16 v[58:61], v[218:221], v[150:153], v[58:61]
	v_mfma_f32_16x16x32_bf16 v[50:53], v[226:229], v[150:153], v[50:53]
	v_mfma_f32_16x16x32_bf16 v[42:45], v[218:221], v[158:161], v[42:45]
	v_mfma_f32_16x16x32_bf16 v[34:37], v[226:229], v[158:161], v[34:37]
	v_mfma_f32_16x16x32_bf16 v[26:29], v[218:221], v[202:205], v[26:29]
	v_mfma_f32_16x16x32_bf16 v[18:21], v[226:229], v[202:205], v[18:21]
	v_mfma_f32_16x16x32_bf16 v[10:13], v[218:221], v[210:213], v[10:13]
	v_mfma_f32_16x16x32_bf16 v[2:5], v[226:229], v[210:213], v[2:5]
	s_add_u32 s0, s0, 0x100
	s_addc_u32 s1, s1, 0
	s_add_u32 s28, s28, 0x100
	s_addc_u32 s29, s29, 0
	s_cmp_ge_i32 s36, s57
	s_mov_b32 s2, s36
	s_barrier
	s_cbranch_scc0 .LBB0_1104
	s_branch .LBB0_1095

.LBB0_1255:
	ds_read_b128 v[146:149], v177
	ds_read_b128 v[150:153], v178
	ds_read_b128 v[154:157], v179
	ds_read_b128 v[158:161], v180
	s_add_i32 s72, s2, 2
	s_add_u32 s28, s26, 0x80
	s_addc_u32 s3, s27, 0
	s_cmp_eq_u32 s64, s2
	s_cselect_b32 s2, s54, s28
	s_cselect_b32 s3, s55, s3
	s_cselect_b32 s29, s1, s53
	s_cselect_b32 s28, s0, s37
	s_mov_b32 m0, s66
	s_nop 0
	global_load_lds_dwordx4 v138, s[26:27]
	s_mov_b32 m0, s67
	s_nop 0
	global_load_lds_dwordx4 v140, s[26:27]
	ds_read_b128 v[164:167], v174
	ds_read_b128 v[168:171], v174 offset:1024
	ds_read_b128 v[194:197], v174 offset:2048
	ds_read_b128 v[198:201], v174 offset:3072
	ds_read_b128 v[206:209], v174 offset:4096
	ds_read_b128 v[210:213], v174 offset:5120
	ds_read_b128 v[214:217], v174 offset:6144
	ds_read_b128 v[218:221], v174 offset:7168
	s_waitcnt lgkmcnt(8)
	s_barrier
	s_waitcnt lgkmcnt(0)
	s_waitcnt lgkmcnt(0)
	v_mfma_f32_16x16x32_bf16 v[130:133], v[146:149], v[164:167], v[130:133]
	v_mfma_f32_16x16x32_bf16 v[126:129], v[154:157], v[164:167], v[126:129]
	v_mfma_f32_16x16x32_bf16 v[114:117], v[146:149], v[194:197], v[114:117]
	v_mfma_f32_16x16x32_bf16 v[110:113], v[154:157], v[194:197], v[110:113]
	v_mfma_f32_16x16x32_bf16 v[98:101], v[146:149], v[206:209], v[98:101]
	v_mfma_f32_16x16x32_bf16 v[94:97], v[154:157], v[206:209], v[94:97]
	v_mfma_f32_16x16x32_bf16 v[82:85], v[146:149], v[214:217], v[82:85]
	v_mfma_f32_16x16x32_bf16 v[78:81], v[154:157], v[214:217], v[78:81]
	v_mfma_f32_16x16x32_bf16 v[130:133], v[150:153], v[168:171], v[130:133]
	v_mfma_f32_16x16x32_bf16 v[126:129], v[158:161], v[168:171], v[126:129]
	v_mfma_f32_16x16x32_bf16 v[114:117], v[150:153], v[198:201], v[114:117]
	v_mfma_f32_16x16x32_bf16 v[110:113], v[158:161], v[198:201], v[110:113]
	v_mfma_f32_16x16x32_bf16 v[98:101], v[150:153], v[210:213], v[98:101]
	v_mfma_f32_16x16x32_bf16 v[94:97], v[158:161], v[210:213], v[94:97]
	v_mfma_f32_16x16x32_bf16 v[82:85], v[150:153], v[218:221], v[82:85]
	v_mfma_f32_16x16x32_bf16 v[78:81], v[158:161], v[218:221], v[78:81]
	s_barrier
	s_mov_b32 m0, s38
	s_nop 0
	global_load_lds_dwordx4 v134, s[28:29]
	s_mov_b32 m0, s39
	s_nop 0
	global_load_lds_dwordx4 v136, s[28:29]
	ds_read_b128 v[222:225], v181
	ds_read_b128 v[226:229], v182
	ds_read_b128 v[230:233], v183
	ds_read_b128 v[234:237], v184
	s_barrier
	s_waitcnt lgkmcnt(0)
	s_waitcnt lgkmcnt(0)
	v_mfma_f32_16x16x32_bf16 v[122:125], v[222:225], v[164:167], v[122:125]
	v_mfma_f32_16x16x32_bf16 v[118:121], v[230:233], v[164:167], v[118:121]
	v_mfma_f32_16x16x32_bf16 v[106:109], v[222:225], v[194:197], v[106:109]
	v_mfma_f32_16x16x32_bf16 v[102:105], v[230:233], v[194:197], v[102:105]
	v_mfma_f32_16x16x32_bf16 v[90:93], v[222:225], v[206:209], v[90:93]
	v_mfma_f32_16x16x32_bf16 v[86:89], v[230:233], v[206:209], v[86:89]
	v_mfma_f32_16x16x32_bf16 v[74:77], v[222:225], v[214:217], v[74:77]
	v_mfma_f32_16x16x32_bf16 v[68:71], v[230:233], v[214:217], v[70:73]
	v_mfma_f32_16x16x32_bf16 v[122:125], v[226:229], v[168:171], v[122:125]
	v_mfma_f32_16x16x32_bf16 v[118:121], v[234:237], v[168:171], v[118:121]
	v_mfma_f32_16x16x32_bf16 v[106:109], v[226:229], v[198:201], v[106:109]
	v_mfma_f32_16x16x32_bf16 v[102:105], v[234:237], v[198:201], v[102:105]
	v_mfma_f32_16x16x32_bf16 v[90:93], v[226:229], v[210:213], v[90:93]
	v_mfma_f32_16x16x32_bf16 v[86:89], v[234:237], v[210:213], v[86:89]
	v_mfma_f32_16x16x32_bf16 v[74:77], v[226:229], v[218:221], v[74:77]
	v_mfma_f32_16x16x32_bf16 v[68:71], v[234:237], v[218:221], v[68:71]
	s_mov_b32 m0, s35
	s_barrier
	global_load_lds_dwordx4 v134, s[2:3]
	s_mov_b32 m0, s40
	s_nop 0
	global_load_lds_dwordx4 v136, s[2:3]
	ds_read_b128 v[164:167], v174 offset:16384
	ds_read_b128 v[168:171], v174 offset:17408
	ds_read_b128 v[194:197], v174 offset:18432
	ds_read_b128 v[198:201], v174 offset:19456
	ds_read_b128 v[206:209], v174 offset:20480
	ds_read_b128 v[210:213], v174 offset:21504
	ds_read_b128 v[214:217], v174 offset:22528
	ds_read_b128 v[218:221], v174 offset:23552
	s_barrier
	s_waitcnt lgkmcnt(0)
	s_waitcnt lgkmcnt(0)
	v_mfma_f32_16x16x32_bf16 v[62:65], v[146:149], v[164:167], v[62:65]
	v_mfma_f32_16x16x32_bf16 v[58:61], v[154:157], v[164:167], v[58:61]
	v_mfma_f32_16x16x32_bf16 v[46:49], v[146:149], v[194:197], v[46:49]
	v_mfma_f32_16x16x32_bf16 v[42:45], v[154:157], v[194:197], v[42:45]
	v_mfma_f32_16x16x32_bf16 v[30:33], v[146:149], v[206:209], v[30:33]
	v_mfma_f32_16x16x32_bf16 v[26:29], v[154:157], v[206:209], v[26:29]
	v_mfma_f32_16x16x32_bf16 v[14:17], v[146:149], v[214:217], v[14:17]
	v_mfma_f32_16x16x32_bf16 v[10:13], v[154:157], v[214:217], v[10:13]
	v_mfma_f32_16x16x32_bf16 v[62:65], v[150:153], v[168:171], v[62:65]
	v_mfma_f32_16x16x32_bf16 v[58:61], v[158:161], v[168:171], v[58:61]
	v_mfma_f32_16x16x32_bf16 v[46:49], v[150:153], v[198:201], v[46:49]
	v_mfma_f32_16x16x32_bf16 v[42:45], v[158:161], v[198:201], v[42:45]
	v_mfma_f32_16x16x32_bf16 v[30:33], v[150:153], v[210:213], v[30:33]
	v_mfma_f32_16x16x32_bf16 v[26:29], v[158:161], v[210:213], v[26:29]
	v_mfma_f32_16x16x32_bf16 v[14:17], v[150:153], v[218:221], v[14:17]
	v_mfma_f32_16x16x32_bf16 v[10:13], v[158:161], v[218:221], v[10:13]
	s_barrier
	s_mov_b32 m0, s41
	s_nop 0
	global_load_lds_dwordx4 v249, s[28:29]
	s_mov_b32 m0, s42
	s_nop 0
	global_load_lds_dwordx4 v248, s[28:29]
	s_waitcnt vmcnt(6)
	s_barrier
	v_mfma_f32_16x16x32_bf16 v[54:57], v[222:225], v[164:167], v[54:57]
	v_mfma_f32_16x16x32_bf16 v[50:53], v[230:233], v[164:167], v[50:53]
	v_mfma_f32_16x16x32_bf16 v[38:41], v[222:225], v[194:197], v[38:41]
	v_mfma_f32_16x16x32_bf16 v[34:37], v[230:233], v[194:197], v[34:37]
	v_mfma_f32_16x16x32_bf16 v[22:25], v[222:225], v[206:209], v[22:25]
	v_mfma_f32_16x16x32_bf16 v[18:21], v[230:233], v[206:209], v[18:21]
	v_mfma_f32_16x16x32_bf16 v[6:9], v[222:225], v[214:217], v[6:9]
	v_mfma_f32_16x16x32_bf16 v[2:5], v[230:233], v[214:217], v[2:5]
	v_mfma_f32_16x16x32_bf16 v[54:57], v[226:229], v[168:171], v[54:57]
	v_mfma_f32_16x16x32_bf16 v[50:53], v[234:237], v[168:171], v[50:53]
	v_mfma_f32_16x16x32_bf16 v[38:41], v[226:229], v[198:201], v[38:41]
	v_mfma_f32_16x16x32_bf16 v[34:37], v[234:237], v[198:201], v[34:37]
	v_mfma_f32_16x16x32_bf16 v[22:25], v[226:229], v[210:213], v[22:25]
	v_mfma_f32_16x16x32_bf16 v[18:21], v[234:237], v[210:213], v[18:21]
	v_mfma_f32_16x16x32_bf16 v[6:9], v[226:229], v[218:221], v[6:9]
	v_mfma_f32_16x16x32_bf16 v[2:5], v[234:237], v[218:221], v[2:5]
	s_barrier
	ds_read_b128 v[146:149], v185
	ds_read_b128 v[150:153], v186
	ds_read_b128 v[154:157], v187
	ds_read_b128 v[158:161], v188
	s_mov_b32 m0, s43
	s_nop 0
	global_load_lds_dwordx4 v249, s[2:3]
	s_mov_b32 m0, s45
	s_nop 0
	global_load_lds_dwordx4 v248, s[2:3]
	ds_read_b128 v[164:167], v174 offset:32768
	ds_read_b128 v[168:171], v174 offset:33792
	ds_read_b128 v[194:197], v174 offset:34816
	ds_read_b128 v[198:201], v174 offset:35840
	ds_read_b128 v[206:209], v174 offset:36864
	ds_read_b128 v[210:213], v174 offset:37888
	ds_read_b128 v[214:217], v174 offset:38912
	ds_read_b128 v[218:221], v174 offset:39936
	s_waitcnt lgkmcnt(8)
	s_barrier
	s_waitcnt lgkmcnt(0)
	s_waitcnt lgkmcnt(0)
	v_mfma_f32_16x16x32_bf16 v[130:133], v[146:149], v[164:167], v[130:133]
	v_mfma_f32_16x16x32_bf16 v[126:129], v[154:157], v[164:167], v[126:129]
	v_mfma_f32_16x16x32_bf16 v[114:117], v[146:149], v[194:197], v[114:117]
	v_mfma_f32_16x16x32_bf16 v[110:113], v[154:157], v[194:197], v[110:113]
	v_mfma_f32_16x16x32_bf16 v[98:101], v[146:149], v[206:209], v[98:101]
	v_mfma_f32_16x16x32_bf16 v[94:97], v[154:157], v[206:209], v[94:97]
	v_mfma_f32_16x16x32_bf16 v[82:85], v[146:149], v[214:217], v[82:85]
	v_mfma_f32_16x16x32_bf16 v[78:81], v[154:157], v[214:217], v[78:81]
	v_mfma_f32_16x16x32_bf16 v[130:133], v[150:153], v[168:171], v[130:133]
	v_mfma_f32_16x16x32_bf16 v[126:129], v[158:161], v[168:171], v[126:129]
	v_mfma_f32_16x16x32_bf16 v[114:117], v[150:153], v[198:201], v[114:117]
	v_mfma_f32_16x16x32_bf16 v[110:113], v[158:161], v[198:201], v[110:113]
	v_mfma_f32_16x16x32_bf16 v[98:101], v[150:153], v[210:213], v[98:101]
	v_mfma_f32_16x16x32_bf16 v[94:97], v[158:161], v[210:213], v[94:97]
	v_mfma_f32_16x16x32_bf16 v[82:85], v[150:153], v[218:221], v[82:85]
	v_mfma_f32_16x16x32_bf16 v[78:81], v[158:161], v[218:221], v[78:81]
	s_barrier
	s_sub_u32 m0, s50, 0x80
	s_nop 0
	global_load_lds_dwordx4 v134, s[28:29] offset:128
	s_sub_u32 m0, s51, 0x80
	s_nop 0
	global_load_lds_dwordx4 v136, s[28:29] offset:128
	ds_read_b128 v[222:225], v189
	ds_read_b128 v[226:229], v190
	ds_read_b128 v[230:233], v191
	ds_read_b128 v[234:237], v192
	s_barrier
	s_waitcnt lgkmcnt(0)
	s_waitcnt lgkmcnt(0)
	v_mfma_f32_16x16x32_bf16 v[122:125], v[222:225], v[164:167], v[122:125]
	v_mfma_f32_16x16x32_bf16 v[118:121], v[230:233], v[164:167], v[118:121]
	v_mfma_f32_16x16x32_bf16 v[106:109], v[222:225], v[194:197], v[106:109]
	v_mfma_f32_16x16x32_bf16 v[102:105], v[230:233], v[194:197], v[102:105]
	v_mfma_f32_16x16x32_bf16 v[90:93], v[222:225], v[206:209], v[90:93]
	v_mfma_f32_16x16x32_bf16 v[86:89], v[230:233], v[206:209], v[86:89]
	v_mfma_f32_16x16x32_bf16 v[72:75], v[222:225], v[214:217], v[74:77]
	v_mfma_f32_16x16x32_bf16 v[68:71], v[230:233], v[214:217], v[68:71]
	v_mfma_f32_16x16x32_bf16 v[122:125], v[226:229], v[168:171], v[122:125]
	v_mfma_f32_16x16x32_bf16 v[118:121], v[234:237], v[168:171], v[118:121]
	v_mfma_f32_16x16x32_bf16 v[106:109], v[226:229], v[198:201], v[106:109]
	v_mfma_f32_16x16x32_bf16 v[102:105], v[234:237], v[198:201], v[102:105]
	v_mfma_f32_16x16x32_bf16 v[90:93], v[226:229], v[210:213], v[90:93]
	v_mfma_f32_16x16x32_bf16 v[86:89], v[234:237], v[210:213], v[86:89]
	v_mfma_f32_16x16x32_bf16 v[74:77], v[226:229], v[218:221], v[72:75]
	v_mfma_f32_16x16x32_bf16 v[70:73], v[234:237], v[218:221], v[68:71]
	s_sub_u32 m0, s60, 0x80
	s_nop 0
	s_barrier
	global_load_lds_dwordx4 v134, s[2:3] offset:128
	s_sub_u32 m0, s61, 0x80
	s_nop 0
	global_load_lds_dwordx4 v136, s[2:3] offset:128
	ds_read_b128 v[164:167], v174 offset:49152
	ds_read_b128 v[168:171], v174 offset:50176
	ds_read_b128 v[194:197], v174 offset:51200
	ds_read_b128 v[198:201], v174 offset:52224
	ds_read_b128 v[206:209], v174 offset:53248
	ds_read_b128 v[210:213], v174 offset:54272
	ds_read_b128 v[214:217], v174 offset:55296
	ds_read_b128 v[218:221], v174 offset:56320
	s_barrier
	s_waitcnt lgkmcnt(0)
	s_waitcnt lgkmcnt(0)
	v_mfma_f32_16x16x32_bf16 v[62:65], v[146:149], v[164:167], v[62:65]
	v_mfma_f32_16x16x32_bf16 v[58:61], v[154:157], v[164:167], v[58:61]
	v_mfma_f32_16x16x32_bf16 v[46:49], v[146:149], v[194:197], v[46:49]
	v_mfma_f32_16x16x32_bf16 v[42:45], v[154:157], v[194:197], v[42:45]
	v_mfma_f32_16x16x32_bf16 v[30:33], v[146:149], v[206:209], v[30:33]
	v_mfma_f32_16x16x32_bf16 v[26:29], v[154:157], v[206:209], v[26:29]
	v_mfma_f32_16x16x32_bf16 v[14:17], v[146:149], v[214:217], v[14:17]
	v_mfma_f32_16x16x32_bf16 v[10:13], v[154:157], v[214:217], v[10:13]
	v_mfma_f32_16x16x32_bf16 v[62:65], v[150:153], v[168:171], v[62:65]
	v_mfma_f32_16x16x32_bf16 v[58:61], v[158:161], v[168:171], v[58:61]
	v_mfma_f32_16x16x32_bf16 v[46:49], v[150:153], v[198:201], v[46:49]
	v_mfma_f32_16x16x32_bf16 v[42:45], v[158:161], v[198:201], v[42:45]
	v_mfma_f32_16x16x32_bf16 v[30:33], v[150:153], v[210:213], v[30:33]
	v_mfma_f32_16x16x32_bf16 v[26:29], v[158:161], v[210:213], v[26:29]
	v_mfma_f32_16x16x32_bf16 v[14:17], v[150:153], v[218:221], v[14:17]
	v_mfma_f32_16x16x32_bf16 v[10:13], v[158:161], v[218:221], v[10:13]
	s_barrier
	s_sub_u32 m0, s62, 0x80
	s_nop 0
	global_load_lds_dwordx4 v249, s[28:29] offset:128
	s_sub_u32 m0, s63, 0x80
	s_nop 0
	global_load_lds_dwordx4 v248, s[28:29] offset:128
	s_waitcnt vmcnt(6)
	s_barrier
	v_mfma_f32_16x16x32_bf16 v[54:57], v[222:225], v[164:167], v[54:57]
	v_mfma_f32_16x16x32_bf16 v[50:53], v[230:233], v[164:167], v[50:53]
	v_mfma_f32_16x16x32_bf16 v[38:41], v[222:225], v[194:197], v[38:41]
	v_mfma_f32_16x16x32_bf16 v[34:37], v[230:233], v[194:197], v[34:37]
	v_mfma_f32_16x16x32_bf16 v[22:25], v[222:225], v[206:209], v[22:25]
	v_mfma_f32_16x16x32_bf16 v[18:21], v[230:233], v[206:209], v[18:21]
	v_mfma_f32_16x16x32_bf16 v[6:9], v[222:225], v[214:217], v[6:9]
	v_mfma_f32_16x16x32_bf16 v[2:5], v[230:233], v[214:217], v[2:5]
	v_mfma_f32_16x16x32_bf16 v[54:57], v[226:229], v[168:171], v[54:57]
	v_mfma_f32_16x16x32_bf16 v[50:53], v[234:237], v[168:171], v[50:53]
	v_mfma_f32_16x16x32_bf16 v[38:41], v[226:229], v[198:201], v[38:41]
	v_mfma_f32_16x16x32_bf16 v[34:37], v[234:237], v[198:201], v[34:37]
	v_mfma_f32_16x16x32_bf16 v[22:25], v[226:229], v[210:213], v[22:25]
	v_mfma_f32_16x16x32_bf16 v[18:21], v[234:237], v[210:213], v[18:21]
	v_mfma_f32_16x16x32_bf16 v[6:9], v[226:229], v[218:221], v[6:9]
	v_mfma_f32_16x16x32_bf16 v[2:5], v[234:237], v[218:221], v[2:5]
	s_add_u32 s26, s26, 0x100
	s_addc_u32 s27, s27, 0
	s_add_u32 s37, s37, 0x100
	s_addc_u32 s53, s53, 0
	s_cmp_ge_i32 s72, s49
	s_mov_b32 s2, s72
	s_barrier
	s_cbranch_scc0 .LBB0_1255
